# P4 and P5 K loops: extra s_setprio yield point after every 8 MFMAs
# baseline (speedup 1.0000x reference)
; #define PG8_STAGE(bufoff, gbase, voff) do { _Pragma("unroll") for (int _i = 0; _i < 2; ++_i) \
;         __builtin_amdgcn_global_load_lds((const unsigned*)((const char*)(gbase) + (voff)[_i]), (PG8_LAS unsigned*)(lds + (bufoff) + ldsw + _i * 8192), 16, 0, 0); } while (0)
; #define PG8_LDA(dst, b, h) do { _Pragma("unroll") for (int m = 0; m < 4; ++m) _Pragma("unroll") for (int k = 0; k < 2; ++k) dst[m][k] = *(const PG8_LAS bf16x8*)(lds + PG8_SA(b, h) + aoff + m * 2048 + k * 1024); } while (0)
; #define PG8_LDB(dst, b, h) do { _Pragma("unroll") for (int n = 0; n < 2; ++n) _Pragma("unroll") for (int k = 0; k < 2; ++k) dst[n][k] = *(const PG8_LAS bf16x8*)(lds + PG8_SB(b, h) + boff + n * 2048 + k * 1024); } while (0)
; #define PG8_MMA(ai, bj, At, Bt) do { __builtin_amdgcn_s_setprio(1); _Pragma("unroll") for (int m = 0; m < 4; ++m) _Pragma("unroll") for (int n = 0; n < 2; ++n) _Pragma("unroll") for (int k = 0; k < 2; ++k) \
;         acc[ai][bj][m][n] = __builtin_amdgcn_mfma_f32_16x16x32_bf16(Bt[n][k], At[m][k], acc[ai][bj][m][n], 0, 0, 0); __builtin_amdgcn_s_setprio(0); } while (0)
; template <class Epi, class Sched, bool ALIGN_EPI = false, bool SP2 = false, bool ABLK = false>
; __device__ __forceinline__ void gemm_phase(PG8_LAS unsigned char* lds, const Gemm g, const Sched& S, const Epi& E) {
;     ...
;         for (int t = 0; t < nt; t += 2) {
;             if constexpr (Epi::MID) { if (t == nt / 2) E.mid(acc, cur, wr, wc, fr, fq); }
;             const bool last = (t == nt - 2);
;             const char* a1 = cA + (size_t)(t + 1) * kstepA;
;             const char* a2 = last ? nA : cA + (size_t)(t + 2) * kstepA; const char* b2 = last ? nB : cB + (size_t)(t + 2) * kstep;
;             const char* a3 = a2 + kstepA; const char* b3 = b2 + kstep;
;             if (last && has_next) S.a_ready(nxt);
;             if constexpr (SP2) {
;             PG8_LDB(B0, 0, 0); PG8_LDB(B1, 0, 1); PG8_SCHED; PG8_LDA(At, 0, 0); PG8_STAGE(PG8_SA(1, 1), a1 + hstepA, voffA);
;             PG8_WAIT_V(8); PG8_WAIT_L(0); PG8_BAR; PG8_MMA(0, 0, At, B0); PG8_MMA(0, 1, At, B1); PG8_BAR; PG8_SCHED;
;             PG8_LDA(At, 0, 1); PG8_STAGE(PG8_SB(0, 0), b2, voffB); PG8_STAGE(PG8_SB(0, 1), b2 + hstep, voffB); PG8_STAGE(PG8_SA(0, 0), a2, voffA);
;             PG8_WAIT_V(8); PG8_WAIT_L(0); PG8_BAR; PG8_MMA(1, 0, At, B0); PG8_MMA(1, 1, At, B1); PG8_BAR; PG8_SCHED;
.LBB0_578:
	ds_read_b128 v[142:145], v151
	ds_read_b128 v[154:157], v151 offset:1024
	ds_read_b128 v[158:161], v151 offset:2048
	ds_read_b128 v[162:165], v151 offset:3072
	ds_read_b128 v[166:169], v152
	ds_read_b128 v[170:173], v152 offset:1024
	ds_read_b128 v[174:177], v152 offset:2048
	ds_read_b128 v[178:181], v152 offset:3072
	s_add_u32 s36, s34, 0x4000
	s_addc_u32 s37, s35, 0
	s_cmp_eq_u32 s64, 60
	s_cselect_b32 s40, s31, s36
	s_cselect_b32 s41, s21, s37
	s_cselect_b32 s38, s61, s62
	s_cselect_b32 s39, s23, s63
	s_add_u32 s36, s40, 0x8000
	s_addc_u32 s37, s41, 0
	v_lshl_add_u64 v[146:147], s[34:35], 0, v[138:139]
	s_add_i32 m0, s45, 0xc000
	ds_read_b128 v[182:185], v153
	ds_read_b128 v[186:189], v153 offset:1024
	ds_read_b128 v[190:193], v153 offset:2048
	ds_read_b128 v[194:197], v153 offset:3072
	ds_read_b128 v[198:201], v153 offset:4096
	ds_read_b128 v[202:205], v153 offset:5120
	ds_read_b128 v[206:209], v153 offset:6144
	ds_read_b128 v[210:213], v153 offset:7168
	global_load_lds_dwordx4 v[146:147], off
	v_lshl_add_u64 v[146:147], s[34:35], 0, v[140:141]
	s_add_i32 m0, s45, 0xe000
	s_nop 0
	global_load_lds_dwordx4 v[146:147], off
	s_waitcnt vmcnt(8)
	s_waitcnt lgkmcnt(0)
	s_barrier
	s_setprio 1
	s_waitcnt lgkmcnt(0)
	v_mfma_f32_16x16x32_bf16 v[124:127], v[142:145], v[182:185], v[124:127]
	v_mfma_f32_16x16x32_bf16 v[120:123], v[158:161], v[182:185], v[120:123]
	v_mfma_f32_16x16x32_bf16 v[116:119], v[142:145], v[190:193], v[116:119]
	v_mfma_f32_16x16x32_bf16 v[112:115], v[158:161], v[190:193], v[112:115]
	v_mfma_f32_16x16x32_bf16 v[96:99], v[142:145], v[198:201], v[96:99]
	v_mfma_f32_16x16x32_bf16 v[88:91], v[158:161], v[198:201], v[88:91]
	v_mfma_f32_16x16x32_bf16 v[80:83], v[142:145], v[206:209], v[80:83]
	v_mfma_f32_16x16x32_bf16 v[72:75], v[158:161], v[206:209], v[72:75]
	s_setprio 0
	s_setprio 1
	v_mfma_f32_16x16x32_bf16 v[124:127], v[154:157], v[186:189], v[124:127]
	v_mfma_f32_16x16x32_bf16 v[120:123], v[162:165], v[186:189], v[120:123]
	v_mfma_f32_16x16x32_bf16 v[116:119], v[154:157], v[194:197], v[116:119]
	v_mfma_f32_16x16x32_bf16 v[112:115], v[162:165], v[194:197], v[112:115]
	v_mfma_f32_16x16x32_bf16 v[96:99], v[154:157], v[202:205], v[96:99]
	v_mfma_f32_16x16x32_bf16 v[88:91], v[162:165], v[202:205], v[88:91]
	v_mfma_f32_16x16x32_bf16 v[80:83], v[154:157], v[210:213], v[80:83]
	v_mfma_f32_16x16x32_bf16 v[72:75], v[162:165], v[210:213], v[72:75]
	s_setprio 0
	s_setprio 1
	v_mfma_f32_16x16x32_bf16 v[108:111], v[166:169], v[182:185], v[108:111]
	v_mfma_f32_16x16x32_bf16 v[104:107], v[174:177], v[182:185], v[104:107]
	v_mfma_f32_16x16x32_bf16 v[100:103], v[166:169], v[190:193], v[100:103]
	v_mfma_f32_16x16x32_bf16 v[92:95], v[174:177], v[190:193], v[92:95]
	v_mfma_f32_16x16x32_bf16 v[84:87], v[166:169], v[198:201], v[84:87]
	v_mfma_f32_16x16x32_bf16 v[76:79], v[174:177], v[198:201], v[76:79]
	v_mfma_f32_16x16x32_bf16 v[68:71], v[166:169], v[206:209], v[68:71]
	v_mfma_f32_16x16x32_bf16 v[64:67], v[174:177], v[206:209], v[64:67]
	s_setprio 0
	s_setprio 1
	v_mfma_f32_16x16x32_bf16 v[108:111], v[170:173], v[186:189], v[108:111]
	v_mfma_f32_16x16x32_bf16 v[104:107], v[178:181], v[186:189], v[104:107]
	v_mfma_f32_16x16x32_bf16 v[100:103], v[170:173], v[194:197], v[100:103]
	v_mfma_f32_16x16x32_bf16 v[92:95], v[178:181], v[194:197], v[92:95]
	v_mfma_f32_16x16x32_bf16 v[84:87], v[170:173], v[202:205], v[84:87]
	v_mfma_f32_16x16x32_bf16 v[76:79], v[178:181], v[202:205], v[76:79]
	v_mfma_f32_16x16x32_bf16 v[68:71], v[170:173], v[210:213], v[68:71]
	v_mfma_f32_16x16x32_bf16 v[64:67], v[178:181], v[210:213], v[64:67]
	s_setprio 0
	s_barrier
	s_add_i32 s65, s56, s44
	v_lshl_add_u64 v[146:147], s[38:39], 0, v[132:133]
	s_mov_b32 m0, s65
	ds_read_b128 v[182:185], v153 offset:16384
	ds_read_b128 v[186:189], v153 offset:17408
	ds_read_b128 v[190:193], v153 offset:18432
	ds_read_b128 v[194:197], v153 offset:19456
	ds_read_b128 v[198:201], v153 offset:20480
	ds_read_b128 v[202:205], v153 offset:21504
	ds_read_b128 v[206:209], v153 offset:22528
	ds_read_b128 v[210:213], v153 offset:23552
	global_load_lds_dwordx4 v[146:147], off
	s_add_i32 m0, s65, 0x2000
	s_add_u32 s70, s38, 0x100000
	v_lshl_add_u64 v[214:215], s[38:39], 0, v[128:129]
	s_addc_u32 s71, s39, 0
	s_add_i32 s65, s57, s44
	global_load_lds_dwordx4 v[214:215], off
	v_lshl_add_u64 v[216:217], s[70:71], 0, v[132:133]
	s_mov_b32 m0, s65
	s_nop 0
	global_load_lds_dwordx4 v[216:217], off
	v_lshl_add_u64 v[216:217], s[70:71], 0, v[128:129]
	s_add_i32 m0, s65, 0x2000
	s_nop 0
	global_load_lds_dwordx4 v[216:217], off
	v_lshl_add_u64 v[216:217], s[40:41], 0, v[134:135]
	s_mov_b32 m0, s45
	s_nop 0
	global_load_lds_dwordx4 v[216:217], off
	v_lshl_add_u64 v[216:217], s[40:41], 0, v[130:131]
	s_mov_b32 m0, s47
	s_nop 0
	global_load_lds_dwordx4 v[216:217], off
	s_waitcnt vmcnt(8)
	s_waitcnt lgkmcnt(0)
	s_barrier
; #define PG8_STAGE(bufoff, gbase, voff) do { _Pragma("unroll") for (int _i = 0; _i < 2; ++_i) \
;         __builtin_amdgcn_global_load_lds((const unsigned*)((const char*)(gbase) + (voff)[_i]), (PG8_LAS unsigned*)(lds + (bufoff) + ldsw + _i * 8192), 16, 0, 0); } while (0)
; #define PG8_LDA(dst, b, h) do { _Pragma("unroll") for (int m = 0; m < 4; ++m) _Pragma("unroll") for (int k = 0; k < 2; ++k) dst[m][k] = *(const PG8_LAS bf16x8*)(lds + PG8_SA(b, h) + aoff + m * 2048 + k * 1024); } while (0)
; #define PG8_LDB(dst, b, h) do { _Pragma("unroll") for (int n = 0; n < 2; ++n) _Pragma("unroll") for (int k = 0; k < 2; ++k) dst[n][k] = *(const PG8_LAS bf16x8*)(lds + PG8_SB(b, h) + boff + n * 2048 + k * 1024); } while (0)
; #define PG8_MMA(ai, bj, At, Bt) do { __builtin_amdgcn_s_setprio(1); _Pragma("unroll") for (int m = 0; m < 4; ++m) _Pragma("unroll") for (int n = 0; n < 2; ++n) _Pragma("unroll") for (int k = 0; k < 2; ++k) \
;         acc[ai][bj][m][n] = __builtin_amdgcn_mfma_f32_16x16x32_bf16(Bt[n][k], At[m][k], acc[ai][bj][m][n], 0, 0, 0); __builtin_amdgcn_s_setprio(0); } while (0)
; #define PG8_WAIT_V(n) asm volatile("s_waitcnt vmcnt(" #n ")" ::: "memory")
; #define PG8_WAIT_L(n) asm volatile("s_waitcnt lgkmcnt(" #n ")" ::: "memory")
; #define PG8_BAR __builtin_amdgcn_s_barrier()
; #define PG8_SCHED __builtin_amdgcn_sched_barrier(0)
; template <class Epi, class Sched, bool ALIGN_EPI = false, bool SP2 = false, bool ABLK = false>
; __device__ __forceinline__ void gemm_phase(PG8_LAS unsigned char* lds, const Gemm g, const Sched& S, const Epi& E) {
;     ...
;             PG8_WAIT_V(8); PG8_WAIT_L(0); PG8_BAR; PG8_MMA(1, 0, At, B0); PG8_MMA(1, 1, At, B1); PG8_BAR; PG8_SCHED;
;             PG8_LDB(B0, 1, 0); PG8_LDB(B1, 1, 1); PG8_SCHED; PG8_LDA(At, 1, 0); PG8_STAGE(PG8_SA(0, 1), a2 + hstepA, voffA);
;             PG8_WAIT_V(8); PG8_WAIT_L(0); PG8_BAR; PG8_MMA(0, 0, At, B0); PG8_MMA(0, 1, At, B1); PG8_BAR; PG8_SCHED;
	s_setprio 1
	s_waitcnt lgkmcnt(0)
	v_mfma_f32_16x16x32_bf16 v[60:63], v[142:145], v[182:185], v[60:63]
	v_mfma_f32_16x16x32_bf16 v[56:59], v[158:161], v[182:185], v[56:59]
	v_mfma_f32_16x16x32_bf16 v[48:51], v[142:145], v[190:193], v[48:51]
	v_mfma_f32_16x16x32_bf16 v[40:43], v[158:161], v[190:193], v[40:43]
	v_mfma_f32_16x16x32_bf16 v[32:35], v[142:145], v[198:201], v[32:35]
	v_mfma_f32_16x16x32_bf16 v[24:27], v[158:161], v[198:201], v[24:27]
	v_mfma_f32_16x16x32_bf16 v[16:19], v[142:145], v[206:209], v[16:19]
	v_mfma_f32_16x16x32_bf16 v[8:11], v[158:161], v[206:209], v[8:11]
	s_setprio 0
	s_setprio 1
	v_mfma_f32_16x16x32_bf16 v[60:63], v[154:157], v[186:189], v[60:63]
	v_mfma_f32_16x16x32_bf16 v[56:59], v[162:165], v[186:189], v[56:59]
	v_mfma_f32_16x16x32_bf16 v[48:51], v[154:157], v[194:197], v[48:51]
	v_mfma_f32_16x16x32_bf16 v[40:43], v[162:165], v[194:197], v[40:43]
	v_mfma_f32_16x16x32_bf16 v[32:35], v[154:157], v[202:205], v[32:35]
	v_mfma_f32_16x16x32_bf16 v[24:27], v[162:165], v[202:205], v[24:27]
	v_mfma_f32_16x16x32_bf16 v[16:19], v[154:157], v[210:213], v[16:19]
	v_mfma_f32_16x16x32_bf16 v[8:11], v[162:165], v[210:213], v[8:11]
	s_setprio 0
	s_setprio 1
	v_mfma_f32_16x16x32_bf16 v[52:55], v[166:169], v[182:185], v[52:55]
	v_mfma_f32_16x16x32_bf16 v[44:47], v[174:177], v[182:185], v[44:47]
	v_mfma_f32_16x16x32_bf16 v[36:39], v[166:169], v[190:193], v[36:39]
	v_mfma_f32_16x16x32_bf16 v[28:31], v[174:177], v[190:193], v[28:31]
	v_mfma_f32_16x16x32_bf16 v[20:23], v[166:169], v[198:201], v[20:23]
	v_mfma_f32_16x16x32_bf16 v[12:15], v[174:177], v[198:201], v[12:15]
	v_mfma_f32_16x16x32_bf16 v[4:7], v[166:169], v[206:209], v[4:7]
	v_mfma_f32_16x16x32_bf16 v[0:3], v[174:177], v[206:209], v[0:3]
	s_setprio 0
	s_setprio 1
	v_mfma_f32_16x16x32_bf16 v[52:55], v[170:173], v[186:189], v[52:55]
	v_mfma_f32_16x16x32_bf16 v[44:47], v[178:181], v[186:189], v[44:47]
	v_mfma_f32_16x16x32_bf16 v[36:39], v[170:173], v[194:197], v[36:39]
	v_mfma_f32_16x16x32_bf16 v[28:31], v[178:181], v[194:197], v[28:31]
	v_mfma_f32_16x16x32_bf16 v[20:23], v[170:173], v[202:205], v[20:23]
	v_mfma_f32_16x16x32_bf16 v[12:15], v[178:181], v[202:205], v[12:15]
	v_mfma_f32_16x16x32_bf16 v[4:7], v[170:173], v[210:213], v[4:7]
	v_mfma_f32_16x16x32_bf16 v[0:3], v[178:181], v[210:213], v[0:3]
	s_setprio 0
	s_barrier
	s_add_i32 s65, 0, 0x18000
	v_add_u32_e32 v136, s65, v150
	s_add_i32 s68, 0, 0x1c000
	ds_read_b128 v[142:145], v136
	ds_read_b128 v[154:157], v136 offset:1024
	ds_read_b128 v[158:161], v136 offset:2048
	ds_read_b128 v[162:165], v136 offset:3072
	v_add_u32_e32 v136, s68, v150
	ds_read_b128 v[166:169], v136
	ds_read_b128 v[170:173], v136 offset:1024
	ds_read_b128 v[174:177], v136 offset:2048
	ds_read_b128 v[178:181], v136 offset:3072
	s_add_u32 s40, s40, 0x4000
	s_addc_u32 s41, s41, 0
	s_mov_b32 m0, s48
	v_lshl_add_u64 v[216:217], s[40:41], 0, v[134:135]
	ds_read_b128 v[182:185], v153 offset:32768
	ds_read_b128 v[186:189], v153 offset:33792
	ds_read_b128 v[190:193], v153 offset:34816
	ds_read_b128 v[194:197], v153 offset:35840
	ds_read_b128 v[198:201], v153 offset:36864
	ds_read_b128 v[202:205], v153 offset:37888
	ds_read_b128 v[206:209], v153 offset:38912
	ds_read_b128 v[210:213], v153 offset:39936
	global_load_lds_dwordx4 v[216:217], off
	v_lshl_add_u64 v[216:217], s[40:41], 0, v[130:131]
	s_mov_b32 m0, s49
	s_nop 0
	global_load_lds_dwordx4 v[216:217], off
	s_waitcnt vmcnt(8)
	s_waitcnt lgkmcnt(0)
	s_barrier
	s_setprio 1
	s_waitcnt lgkmcnt(0)
	v_mfma_f32_16x16x32_bf16 v[124:127], v[142:145], v[182:185], v[124:127]
	v_mfma_f32_16x16x32_bf16 v[120:123], v[158:161], v[182:185], v[120:123]
	v_mfma_f32_16x16x32_bf16 v[116:119], v[142:145], v[190:193], v[116:119]
	v_mfma_f32_16x16x32_bf16 v[112:115], v[158:161], v[190:193], v[112:115]
	v_mfma_f32_16x16x32_bf16 v[96:99], v[142:145], v[198:201], v[96:99]
	v_mfma_f32_16x16x32_bf16 v[88:91], v[158:161], v[198:201], v[88:91]
	v_mfma_f32_16x16x32_bf16 v[80:83], v[142:145], v[206:209], v[80:83]
	v_mfma_f32_16x16x32_bf16 v[72:75], v[158:161], v[206:209], v[72:75]
	s_setprio 0
	s_setprio 1
	v_mfma_f32_16x16x32_bf16 v[124:127], v[154:157], v[186:189], v[124:127]
	v_mfma_f32_16x16x32_bf16 v[120:123], v[162:165], v[186:189], v[120:123]
	v_mfma_f32_16x16x32_bf16 v[116:119], v[154:157], v[194:197], v[116:119]
	v_mfma_f32_16x16x32_bf16 v[112:115], v[162:165], v[194:197], v[112:115]
	v_mfma_f32_16x16x32_bf16 v[96:99], v[154:157], v[202:205], v[96:99]
	v_mfma_f32_16x16x32_bf16 v[88:91], v[162:165], v[202:205], v[88:91]
	v_mfma_f32_16x16x32_bf16 v[80:83], v[154:157], v[210:213], v[80:83]
	v_mfma_f32_16x16x32_bf16 v[72:75], v[162:165], v[210:213], v[72:75]
	s_setprio 0
	s_setprio 1
	v_mfma_f32_16x16x32_bf16 v[108:111], v[166:169], v[182:185], v[108:111]
	v_mfma_f32_16x16x32_bf16 v[104:107], v[174:177], v[182:185], v[104:107]
	v_mfma_f32_16x16x32_bf16 v[100:103], v[166:169], v[190:193], v[100:103]
	v_mfma_f32_16x16x32_bf16 v[92:95], v[174:177], v[190:193], v[92:95]
	v_mfma_f32_16x16x32_bf16 v[84:87], v[166:169], v[198:201], v[84:87]
	v_mfma_f32_16x16x32_bf16 v[76:79], v[174:177], v[198:201], v[76:79]
	v_mfma_f32_16x16x32_bf16 v[68:71], v[166:169], v[206:209], v[68:71]
	v_mfma_f32_16x16x32_bf16 v[64:67], v[174:177], v[206:209], v[64:67]
	s_setprio 0
	s_setprio 1
	v_mfma_f32_16x16x32_bf16 v[108:111], v[170:173], v[186:189], v[108:111]
	v_mfma_f32_16x16x32_bf16 v[104:107], v[178:181], v[186:189], v[104:107]
	v_mfma_f32_16x16x32_bf16 v[100:103], v[170:173], v[194:197], v[100:103]
	v_mfma_f32_16x16x32_bf16 v[92:95], v[178:181], v[194:197], v[92:95]
	v_mfma_f32_16x16x32_bf16 v[84:87], v[170:173], v[202:205], v[84:87]
	v_mfma_f32_16x16x32_bf16 v[76:79], v[178:181], v[202:205], v[76:79]
	v_mfma_f32_16x16x32_bf16 v[68:71], v[170:173], v[210:213], v[68:71]
	v_mfma_f32_16x16x32_bf16 v[64:67], v[178:181], v[210:213], v[64:67]
	s_setprio 0
	s_barrier
; #define PG8_STAGE(bufoff, gbase, voff) do { _Pragma("unroll") for (int _i = 0; _i < 2; ++_i) \
;         __builtin_amdgcn_global_load_lds((const unsigned*)((const char*)(gbase) + (voff)[_i]), (PG8_LAS unsigned*)(lds + (bufoff) + ldsw + _i * 8192), 16, 0, 0); } while (0)
; #define PG8_LDA(dst, b, h) do { _Pragma("unroll") for (int m = 0; m < 4; ++m) _Pragma("unroll") for (int k = 0; k < 2; ++k) dst[m][k] = *(const PG8_LAS bf16x8*)(lds + PG8_SA(b, h) + aoff + m * 2048 + k * 1024); } while (0)
; #define PG8_MMA(ai, bj, At, Bt) do { __builtin_amdgcn_s_setprio(1); _Pragma("unroll") for (int m = 0; m < 4; ++m) _Pragma("unroll") for (int n = 0; n < 2; ++n) _Pragma("unroll") for (int k = 0; k < 2; ++k) \
;         acc[ai][bj][m][n] = __builtin_amdgcn_mfma_f32_16x16x32_bf16(Bt[n][k], At[m][k], acc[ai][bj][m][n], 0, 0, 0); __builtin_amdgcn_s_setprio(0); } while (0)
; #define PG8_WAIT_V(n) asm volatile("s_waitcnt vmcnt(" #n ")" ::: "memory")
; #define PG8_WAIT_L(n) asm volatile("s_waitcnt lgkmcnt(" #n ")" ::: "memory")
; #define PG8_BAR __builtin_amdgcn_s_barrier()
; #define PG8_SCHED __builtin_amdgcn_sched_barrier(0)
; template <class Epi, class Sched, bool ALIGN_EPI = false, bool SP2 = false, bool ABLK = false>
; __device__ __forceinline__ void gemm_phase(PG8_LAS unsigned char* lds, const Gemm g, const Sched& S, const Epi& E) {
;     ...
;             PG8_LDA(At, 1, 1); PG8_STAGE(PG8_SB(1, 0), b3, voffB); PG8_STAGE(PG8_SB(1, 1), b3 + hstep, voffB); PG8_STAGE(PG8_SA(1, 0), a3, voffA);
;             PG8_WAIT_V(8); PG8_WAIT_L(0); PG8_BAR; PG8_MMA(1, 0, At, B0); PG8_MMA(1, 1, At, B1); PG8_BAR; PG8_SCHED;
	s_add_i32 s40, s65, s44
	v_lshl_add_u64 v[146:147], v[146:147], 0, s[4:5]
	s_mov_b32 m0, s40
	ds_read_b128 v[182:185], v153 offset:49152
	ds_read_b128 v[186:189], v153 offset:50176
	ds_read_b128 v[190:193], v153 offset:51200
	ds_read_b128 v[194:197], v153 offset:52224
	ds_read_b128 v[198:201], v153 offset:53248
	ds_read_b128 v[202:205], v153 offset:54272
	ds_read_b128 v[206:209], v153 offset:55296
	ds_read_b128 v[210:213], v153 offset:56320
	global_load_lds_dwordx4 v[146:147], off
	s_add_i32 m0, s40, 0x2000
	s_add_u32 s38, s38, 0x100080
	v_lshl_add_u64 v[146:147], v[214:215], 0, s[4:5]
	s_addc_u32 s39, s39, 0
	s_add_i32 s40, s68, s44
	global_load_lds_dwordx4 v[146:147], off
	v_lshl_add_u64 v[146:147], s[38:39], 0, v[132:133]
	s_mov_b32 m0, s40
	s_nop 0
	global_load_lds_dwordx4 v[146:147], off
	v_lshl_add_u64 v[146:147], s[38:39], 0, v[128:129]
	s_add_i32 m0, s40, 0x2000
	s_nop 0
	global_load_lds_dwordx4 v[146:147], off
	v_lshl_add_u64 v[146:147], s[36:37], 0, v[134:135]
	s_mov_b32 m0, s54
	s_nop 0
	global_load_lds_dwordx4 v[146:147], off
	v_lshl_add_u64 v[146:147], s[36:37], 0, v[130:131]
	s_mov_b32 m0, s55
	s_nop 0
	global_load_lds_dwordx4 v[146:147], off
	s_waitcnt vmcnt(8)
	s_waitcnt lgkmcnt(0)
	s_barrier
	s_setprio 1
	s_waitcnt lgkmcnt(0)
	v_mfma_f32_16x16x32_bf16 v[60:63], v[142:145], v[182:185], v[60:63]
	v_mfma_f32_16x16x32_bf16 v[56:59], v[158:161], v[182:185], v[56:59]
	v_mfma_f32_16x16x32_bf16 v[48:51], v[142:145], v[190:193], v[48:51]
	v_mfma_f32_16x16x32_bf16 v[40:43], v[158:161], v[190:193], v[40:43]
	v_mfma_f32_16x16x32_bf16 v[32:35], v[142:145], v[198:201], v[32:35]
	v_mfma_f32_16x16x32_bf16 v[24:27], v[158:161], v[198:201], v[24:27]
	v_mfma_f32_16x16x32_bf16 v[16:19], v[142:145], v[206:209], v[16:19]
	v_mfma_f32_16x16x32_bf16 v[8:11], v[158:161], v[206:209], v[8:11]
	s_setprio 0
	s_setprio 1
	v_mfma_f32_16x16x32_bf16 v[60:63], v[154:157], v[186:189], v[60:63]
	v_mfma_f32_16x16x32_bf16 v[56:59], v[162:165], v[186:189], v[56:59]
	v_mfma_f32_16x16x32_bf16 v[48:51], v[154:157], v[194:197], v[48:51]
	v_mfma_f32_16x16x32_bf16 v[40:43], v[162:165], v[194:197], v[40:43]
	v_mfma_f32_16x16x32_bf16 v[32:35], v[154:157], v[202:205], v[32:35]
	v_mfma_f32_16x16x32_bf16 v[24:27], v[162:165], v[202:205], v[24:27]
	v_mfma_f32_16x16x32_bf16 v[16:19], v[154:157], v[210:213], v[16:19]
	v_mfma_f32_16x16x32_bf16 v[8:11], v[162:165], v[210:213], v[8:11]
	s_setprio 0
	s_setprio 1
	v_mfma_f32_16x16x32_bf16 v[52:55], v[166:169], v[182:185], v[52:55]
	v_mfma_f32_16x16x32_bf16 v[44:47], v[174:177], v[182:185], v[44:47]
	v_mfma_f32_16x16x32_bf16 v[36:39], v[166:169], v[190:193], v[36:39]
	v_mfma_f32_16x16x32_bf16 v[28:31], v[174:177], v[190:193], v[28:31]
	v_mfma_f32_16x16x32_bf16 v[20:23], v[166:169], v[198:201], v[20:23]
	v_mfma_f32_16x16x32_bf16 v[12:15], v[174:177], v[198:201], v[12:15]
	v_mfma_f32_16x16x32_bf16 v[4:7], v[166:169], v[206:209], v[4:7]
	v_mfma_f32_16x16x32_bf16 v[0:3], v[174:177], v[206:209], v[0:3]
	s_setprio 0
	s_setprio 1
	v_mfma_f32_16x16x32_bf16 v[52:55], v[170:173], v[186:189], v[52:55]
	v_mfma_f32_16x16x32_bf16 v[44:47], v[178:181], v[186:189], v[44:47]
	v_mfma_f32_16x16x32_bf16 v[36:39], v[170:173], v[194:197], v[36:39]
	v_mfma_f32_16x16x32_bf16 v[28:31], v[178:181], v[194:197], v[28:31]
	v_mfma_f32_16x16x32_bf16 v[20:23], v[170:173], v[202:205], v[20:23]
	v_mfma_f32_16x16x32_bf16 v[12:15], v[178:181], v[202:205], v[12:15]
	v_mfma_f32_16x16x32_bf16 v[4:7], v[170:173], v[210:213], v[4:7]
	v_mfma_f32_16x16x32_bf16 v[0:3], v[178:181], v[210:213], v[0:3]
	s_setprio 0
	s_barrier
	s_add_i32 s64, s64, 2
	s_add_u32 s62, s62, 0x100
	s_addc_u32 s63, s63, 0
	s_add_u32 s34, s34, 0x10000
	s_addc_u32 s35, s35, 0
	s_cmp_gt_u32 s64, 61
	s_cbranch_scc0 .LBB0_578
